# two-tiles-per-barrier MoBA loop with group 1's DMA pieces issued after 2 MFMAs instead of 8 (larger latency budget)
# baseline (speedup 1.0000x reference)
; #define ATT_LAS __attribute__((address_space(3)))
; #define ATT_MFMA(a, b, c) __builtin_amdgcn_mfma_f32_32x32x16_bf16((a), (b), (c), 0, 0, 0)
; __device__ __forceinline__ void qkt(f32x16& p0, f32x16& p1, lds_cptr kb, const bf16x8* qr, const f32x16& z) {
; #pragma unroll
;     for (int d0 = 0; d0 < 4; ++d0) {
;         const bf16x8 b0 = *(const ATT_LAS bf16x8*)(kb + d0 * 2048);
;         const bf16x8 b1 = *(const ATT_LAS bf16x8*)(kb + d0 * 2048 + 512);
;         if (d0 == 0) { p0 = ATT_MFMA(b0, qr[0], z); p1 = ATT_MFMA(b1, qr[0], z); }
;         else { p0 = ATT_MFMA(b0, qr[d0], p0); p1 = ATT_MFMA(b1, qr[d0], p1); } }
; }
; __device__ __forceinline__ void pv(f32x16* o, int vb, bf16x8 pa0, bf16x8 pa1, bf16x8 pa2, bf16x8 pa3) {
; #pragma unroll
;     for (int d0 = 0; d0 < 2; ++d0) { s16x4 lo[4], hi[4];
; #pragma unroll
;         for (int ks = 0; ks < 4; ++ks) {
;             asm volatile("ds_read_b64_tr_b16 %0,%1 offset:%c2" : "=&v"(lo[ks]) : "v"(vb), "i"(d0 * 4096 + ks * 1024) : "memory");
;             asm volatile("ds_read_b64_tr_b16 %0,%1 offset:%c2" : "=&v"(hi[ks]) : "v"(vb), "i"(d0 * 4096 + ks * 1024 + 512) : "memory"); }
;         asm volatile("s_waitcnt lgkmcnt(0)" ::: "memory"); __builtin_amdgcn_sched_barrier(0);
;     ...
;         o[d0] = ATT_MFMA(pa0, ATT_PK(0), o[d0]);
;         o[d0] = ATT_MFMA(pa1, ATT_PK(1), o[d0]);
;         o[d0] = ATT_MFMA(pa2, ATT_PK(2), o[d0]);
;         o[d0] = ATT_MFMA(pa3, ATT_PK(3), o[d0]);
;     ...
;     }
; }
.Lmb1_A_g1top:
	s_add_i32 s42, s44, 0x2000
	s_add_i32 s98, s44, 0x4000
	s_and_b32 s45, s98, 0x6000
	v_add_u32_e32 v133, s45, v130
	ds_read_b128 v[154:157], v133
	ds_read_b128 v[158:161], v133 offset:512
	ds_read_b128 v[162:165], v133 offset:2048
	ds_read_b128 v[166:169], v133 offset:2560
	ds_read_b128 v[170:173], v133 offset:4096
	ds_read_b128 v[174:177], v133 offset:4608
	ds_read_b128 v[178:181], v133 offset:6144
	ds_read_b128 v[182:185], v133 offset:6656
	s_and_b32 s45, s42, 0x6000
	v_add_u32_e32 v218, s45, v132
	s_add_i32 s98, s34, 2
	s_cmp_ge_i32 s34, s31
	s_cbranch_scc1 .Lmb1_A_near
	v_mfma_f32_32x32x16_bf16 v[16:31], v[108:111], v[186:189], v[16:31]
	v_exp_f32_e32 v64, v64
	v_exp_f32_e32 v48, v48
	v_mfma_f32_32x32x16_bf16 v[16:31], v[104:107], v[190:193], v[16:31]
	v_exp_f32_e32 v65, v65
	v_exp_f32_e32 v49, v49
	v_add_f32_e32 v252, v64, v48
	s_and_b64 vcc, exec, s[6:7]
	s_cbranch_vccnz .Lmb1_A_g0mid
	s_cmp_eq_u32 s37, 0
	s_cbranch_scc1 .Lmb1_f1Am
	s_mov_b32 s45, s37
	s_cmp_ge_u32 s45, s30
	s_cbranch_scc1 .Lmb1_k0Am
	s_mov_b32 s45, s44
	s_and_b32 s45, s45, 0x6000
	s_add_i32 s45, s45, s74
	s_mov_b32 s99, m0
	s_mov_b32 m0, s45
	s_nop 0
	global_load_lds_dwordx4 v[114:115], off
	s_mov_b32 m0, s99

; #define ATT_LAS __attribute__((address_space(3)))
; #define ATT_MFMA(a, b, c) __builtin_amdgcn_mfma_f32_32x32x16_bf16((a), (b), (c), 0, 0, 0)
; __device__ __forceinline__ void qkt(f32x16& p0, f32x16& p1, lds_cptr kb, const bf16x8* qr, const f32x16& z) {
; #pragma unroll
;     for (int d0 = 0; d0 < 4; ++d0) {
;         const bf16x8 b0 = *(const ATT_LAS bf16x8*)(kb + d0 * 2048);
;         const bf16x8 b1 = *(const ATT_LAS bf16x8*)(kb + d0 * 2048 + 512);
;         if (d0 == 0) { p0 = ATT_MFMA(b0, qr[0], z); p1 = ATT_MFMA(b1, qr[0], z); }
;         else { p0 = ATT_MFMA(b0, qr[d0], p0); p1 = ATT_MFMA(b1, qr[d0], p1); } }
; }
; __device__ __forceinline__ void pv(f32x16* o, int vb, bf16x8 pa0, bf16x8 pa1, bf16x8 pa2, bf16x8 pa3) {
; #pragma unroll
;     for (int d0 = 0; d0 < 2; ++d0) { s16x4 lo[4], hi[4];
; #pragma unroll
;         for (int ks = 0; ks < 4; ++ks) {
;             asm volatile("ds_read_b64_tr_b16 %0,%1 offset:%c2" : "=&v"(lo[ks]) : "v"(vb), "i"(d0 * 4096 + ks * 1024) : "memory");
;             asm volatile("ds_read_b64_tr_b16 %0,%1 offset:%c2" : "=&v"(hi[ks]) : "v"(vb), "i"(d0 * 4096 + ks * 1024 + 512) : "memory"); }
;         asm volatile("s_waitcnt lgkmcnt(0)" ::: "memory"); __builtin_amdgcn_sched_barrier(0);
;     ...
;         o[d0] = ATT_MFMA(pa0, ATT_PK(0), o[d0]);
;         o[d0] = ATT_MFMA(pa1, ATT_PK(1), o[d0]);
;         o[d0] = ATT_MFMA(pa2, ATT_PK(2), o[d0]);
;         o[d0] = ATT_MFMA(pa3, ATT_PK(3), o[d0]);
;     ...
;     }
; }
.Lmb1_A_g0mid:
	v_mfma_f32_32x32x16_bf16 v[16:31], v[100:103], v[194:197], v[16:31]
	v_exp_f32_e32 v66, v66
	v_exp_f32_e32 v50, v50
	v_add_f32_e32 v253, v65, v49
	v_add_f32_e32 v252, v252, v253
	v_mfma_f32_32x32x16_bf16 v[16:31], v[96:99], v[198:201], v[16:31]
	v_exp_f32_e32 v67, v67
	v_exp_f32_e32 v51, v51
	v_add_f32_e32 v253, v66, v50
	v_add_f32_e32 v252, v252, v253
	v_mfma_f32_32x32x16_bf16 v[32:47], v[108:111], v[202:205], v[32:47]
	v_exp_f32_e32 v68, v68
	v_exp_f32_e32 v52, v52
	v_add_f32_e32 v253, v67, v51
	v_add_f32_e32 v252, v252, v253
	ds_read_b64_tr_b16 v[186:187], v218
	ds_read_b64_tr_b16 v[188:189], v218 offset:512
	v_mfma_f32_32x32x16_bf16 v[32:47], v[104:107], v[206:209], v[32:47]
	v_exp_f32_e32 v69, v69
	v_exp_f32_e32 v53, v53
	v_add_f32_e32 v253, v68, v52
	v_add_f32_e32 v252, v252, v253
	ds_read_b64_tr_b16 v[190:191], v218 offset:1024
	ds_read_b64_tr_b16 v[192:193], v218 offset:1536
	v_mfma_f32_32x32x16_bf16 v[32:47], v[100:103], v[210:213], v[32:47]
	v_exp_f32_e32 v70, v70
	v_exp_f32_e32 v54, v54
	v_add_f32_e32 v253, v69, v53
	v_add_f32_e32 v252, v252, v253
	ds_read_b64_tr_b16 v[194:195], v218 offset:2048
	ds_read_b64_tr_b16 v[196:197], v218 offset:2560
	v_mfma_f32_32x32x16_bf16 v[32:47], v[96:99], v[214:217], v[32:47]
	v_exp_f32_e32 v71, v71
	v_exp_f32_e32 v55, v55
	v_add_f32_e32 v253, v70, v54
	v_add_f32_e32 v252, v252, v253
	ds_read_b64_tr_b16 v[198:199], v218 offset:3072
	ds_read_b64_tr_b16 v[200:201], v218 offset:3584
	s_waitcnt lgkmcnt(8)
	v_mfma_f32_32x32x16_bf16 v[236:251], v[154:157], v[92:95], v[220:235]
	v_exp_f32_e32 v72, v72
	v_exp_f32_e32 v56, v56
	v_add_f32_e32 v253, v71, v55
	v_add_f32_e32 v252, v252, v253
	v_cvt_pk_bf16_f32 v108, v64, v65
	v_cvt_pk_bf16_f32 v100, v48, v49
	ds_read_b64_tr_b16 v[202:203], v218 offset:4096
	ds_read_b64_tr_b16 v[204:205], v218 offset:4608
	v_mfma_f32_32x32x16_bf16 v[134:149], v[158:161], v[92:95], v[220:235]
	v_exp_f32_e32 v73, v73
	v_exp_f32_e32 v57, v57
	v_add_f32_e32 v253, v72, v56
	v_add_f32_e32 v252, v252, v253
	v_cvt_pk_bf16_f32 v109, v66, v67
	v_cvt_pk_bf16_f32 v101, v50, v51
	ds_read_b64_tr_b16 v[206:207], v218 offset:5120
	ds_read_b64_tr_b16 v[208:209], v218 offset:5632
	v_mfma_f32_32x32x16_bf16 v[236:251], v[162:165], v[88:91], v[236:251]
	v_exp_f32_e32 v74, v74
	v_exp_f32_e32 v58, v58
	v_add_f32_e32 v253, v73, v57
	v_add_f32_e32 v252, v252, v253
	v_cvt_pk_bf16_f32 v110, v68, v69
	v_cvt_pk_bf16_f32 v102, v52, v53
	ds_read_b64_tr_b16 v[210:211], v218 offset:6144
	ds_read_b64_tr_b16 v[212:213], v218 offset:6656
	v_mfma_f32_32x32x16_bf16 v[134:149], v[166:169], v[88:91], v[134:149]
	v_exp_f32_e32 v75, v75
	v_exp_f32_e32 v59, v59
	v_add_f32_e32 v253, v74, v58
	v_add_f32_e32 v252, v252, v253
	v_cvt_pk_bf16_f32 v111, v70, v71
	v_cvt_pk_bf16_f32 v103, v54, v55
	ds_read_b64_tr_b16 v[214:215], v218 offset:7168
	ds_read_b64_tr_b16 v[216:217], v218 offset:7680
	v_mfma_f32_32x32x16_bf16 v[236:251], v[170:173], v[84:87], v[236:251]
	v_exp_f32_e32 v76, v76
	v_exp_f32_e32 v60, v60
	v_add_f32_e32 v253, v75, v59
	v_add_f32_e32 v252, v252, v253
	v_cvt_pk_bf16_f32 v104, v72, v73
	v_cvt_pk_bf16_f32 v96, v56, v57
	v_mfma_f32_32x32x16_bf16 v[134:149], v[174:177], v[84:87], v[134:149]
	v_exp_f32_e32 v77, v77
	v_exp_f32_e32 v61, v61
	v_add_f32_e32 v253, v76, v60
	v_add_f32_e32 v252, v252, v253
	v_cvt_pk_bf16_f32 v105, v74, v75
	v_cvt_pk_bf16_f32 v97, v58, v59
	v_mfma_f32_32x32x16_bf16 v[236:251], v[178:181], v[80:83], v[236:251]
	v_exp_f32_e32 v78, v78
	v_exp_f32_e32 v62, v62
	v_add_f32_e32 v253, v77, v61
	v_add_f32_e32 v252, v252, v253
	v_cvt_pk_bf16_f32 v106, v76, v77
	v_cvt_pk_bf16_f32 v98, v60, v61
	v_mfma_f32_32x32x16_bf16 v[134:149], v[182:185], v[80:83], v[134:149]
	v_exp_f32_e32 v79, v79
	v_exp_f32_e32 v63, v63
	v_add_f32_e32 v253, v78, v62
	v_add_f32_e32 v252, v252, v253
	v_add_f32_e32 v253, v79, v63
	v_add_f32_e32 v252, v252, v253
	v_cvt_pk_bf16_f32 v107, v78, v79
	v_cvt_pk_bf16_f32 v99, v62, v63
	v_add_f32_e32 v131, v131, v252

; #define ATT_LAS __attribute__((address_space(3)))
; #define ATT_MFMA(a, b, c) __builtin_amdgcn_mfma_f32_32x32x16_bf16((a), (b), (c), 0, 0, 0)
; __device__ __forceinline__ void qkt(f32x16& p0, f32x16& p1, lds_cptr kb, const bf16x8* qr, const f32x16& z) {
; #pragma unroll
;     for (int d0 = 0; d0 < 4; ++d0) {
;         const bf16x8 b0 = *(const ATT_LAS bf16x8*)(kb + d0 * 2048);
;         const bf16x8 b1 = *(const ATT_LAS bf16x8*)(kb + d0 * 2048 + 512);
;         if (d0 == 0) { p0 = ATT_MFMA(b0, qr[0], z); p1 = ATT_MFMA(b1, qr[0], z); }
;         else { p0 = ATT_MFMA(b0, qr[d0], p0); p1 = ATT_MFMA(b1, qr[d0], p1); } }
; }
; __device__ __forceinline__ void pv(f32x16* o, int vb, bf16x8 pa0, bf16x8 pa1, bf16x8 pa2, bf16x8 pa3) {
; #pragma unroll
;     for (int d0 = 0; d0 < 2; ++d0) { s16x4 lo[4], hi[4];
; #pragma unroll
;         for (int ks = 0; ks < 4; ++ks) {
;             asm volatile("ds_read_b64_tr_b16 %0,%1 offset:%c2" : "=&v"(lo[ks]) : "v"(vb), "i"(d0 * 4096 + ks * 1024) : "memory");
;             asm volatile("ds_read_b64_tr_b16 %0,%1 offset:%c2" : "=&v"(hi[ks]) : "v"(vb), "i"(d0 * 4096 + ks * 1024 + 512) : "memory"); }
;         asm volatile("s_waitcnt lgkmcnt(0)" ::: "memory"); __builtin_amdgcn_sched_barrier(0);
;     ...
;         o[d0] = ATT_MFMA(pa0, ATT_PK(0), o[d0]);
;         o[d0] = ATT_MFMA(pa1, ATT_PK(1), o[d0]);
;         o[d0] = ATT_MFMA(pa2, ATT_PK(2), o[d0]);
;         o[d0] = ATT_MFMA(pa3, ATT_PK(3), o[d0]);
;     ...
;     }
; }
.Lmb1_B_g1top:
	s_add_i32 s42, s44, 0x2000
	s_add_i32 s98, s44, 0x4000
	s_and_b32 s45, s98, 0x6000
	v_add_u32_e32 v133, s45, v130
	ds_read_b128 v[154:157], v133
	ds_read_b128 v[158:161], v133 offset:512
	ds_read_b128 v[162:165], v133 offset:2048
	ds_read_b128 v[166:169], v133 offset:2560
	ds_read_b128 v[170:173], v133 offset:4096
	ds_read_b128 v[174:177], v133 offset:4608
	ds_read_b128 v[178:181], v133 offset:6144
	ds_read_b128 v[182:185], v133 offset:6656
	s_and_b32 s45, s42, 0x6000
	v_add_u32_e32 v218, s45, v132
	s_add_i32 s98, s34, 2
	s_cmp_ge_i32 s34, s31
	s_cbranch_scc1 .Lmb1_B_near
	v_mfma_f32_32x32x16_bf16 v[16:31], v[108:111], v[186:189], v[16:31]
	v_exp_f32_e32 v236, v236
	v_exp_f32_e32 v134, v134
	v_mfma_f32_32x32x16_bf16 v[16:31], v[104:107], v[190:193], v[16:31]
	v_exp_f32_e32 v237, v237
	v_exp_f32_e32 v135, v135
	v_add_f32_e32 v252, v236, v134
	s_and_b64 vcc, exec, s[6:7]
	s_cbranch_vccnz .Lmb1_B_g0mid
.Lmb1_B_g0mid:
	v_mfma_f32_32x32x16_bf16 v[16:31], v[100:103], v[194:197], v[16:31]
	v_exp_f32_e32 v238, v238
	v_exp_f32_e32 v136, v136
	v_add_f32_e32 v253, v237, v135
	v_add_f32_e32 v252, v252, v253
	v_mfma_f32_32x32x16_bf16 v[16:31], v[96:99], v[198:201], v[16:31]
	v_exp_f32_e32 v239, v239
	v_exp_f32_e32 v137, v137
	v_add_f32_e32 v253, v238, v136
	v_add_f32_e32 v252, v252, v253
	v_mfma_f32_32x32x16_bf16 v[32:47], v[108:111], v[202:205], v[32:47]
	v_exp_f32_e32 v240, v240
	v_exp_f32_e32 v138, v138
	v_add_f32_e32 v253, v239, v137
	v_add_f32_e32 v252, v252, v253
	ds_read_b64_tr_b16 v[186:187], v218
	ds_read_b64_tr_b16 v[188:189], v218 offset:512
	v_mfma_f32_32x32x16_bf16 v[32:47], v[104:107], v[206:209], v[32:47]
	v_exp_f32_e32 v241, v241
	v_exp_f32_e32 v139, v139
	v_add_f32_e32 v253, v240, v138
	v_add_f32_e32 v252, v252, v253
	ds_read_b64_tr_b16 v[190:191], v218 offset:1024
	ds_read_b64_tr_b16 v[192:193], v218 offset:1536
	v_mfma_f32_32x32x16_bf16 v[32:47], v[100:103], v[210:213], v[32:47]
	v_exp_f32_e32 v242, v242
	v_exp_f32_e32 v140, v140
	v_add_f32_e32 v253, v241, v139
	v_add_f32_e32 v252, v252, v253
	ds_read_b64_tr_b16 v[194:195], v218 offset:2048
	ds_read_b64_tr_b16 v[196:197], v218 offset:2560
	v_mfma_f32_32x32x16_bf16 v[32:47], v[96:99], v[214:217], v[32:47]
	v_exp_f32_e32 v243, v243
	v_exp_f32_e32 v141, v141
	v_add_f32_e32 v253, v242, v140
	v_add_f32_e32 v252, v252, v253
	ds_read_b64_tr_b16 v[198:199], v218 offset:3072
	ds_read_b64_tr_b16 v[200:201], v218 offset:3584
	s_waitcnt lgkmcnt(8)
	v_mfma_f32_32x32x16_bf16 v[64:79], v[154:157], v[92:95], v[220:235]
	v_exp_f32_e32 v244, v244
	v_exp_f32_e32 v142, v142
	v_add_f32_e32 v253, v243, v141
	v_add_f32_e32 v252, v252, v253
	v_cvt_pk_bf16_f32 v108, v236, v237
	v_cvt_pk_bf16_f32 v100, v134, v135
	ds_read_b64_tr_b16 v[202:203], v218 offset:4096
	ds_read_b64_tr_b16 v[204:205], v218 offset:4608
	v_mfma_f32_32x32x16_bf16 v[48:63], v[158:161], v[92:95], v[220:235]
	v_exp_f32_e32 v245, v245
	v_exp_f32_e32 v143, v143
	v_add_f32_e32 v253, v244, v142
	v_add_f32_e32 v252, v252, v253
	v_cvt_pk_bf16_f32 v109, v238, v239
	v_cvt_pk_bf16_f32 v101, v136, v137
	ds_read_b64_tr_b16 v[206:207], v218 offset:5120
	ds_read_b64_tr_b16 v[208:209], v218 offset:5632
	v_mfma_f32_32x32x16_bf16 v[64:79], v[162:165], v[88:91], v[64:79]
	v_exp_f32_e32 v246, v246
	v_exp_f32_e32 v144, v144
	v_add_f32_e32 v253, v245, v143
	v_add_f32_e32 v252, v252, v253
	v_cvt_pk_bf16_f32 v110, v240, v241
	v_cvt_pk_bf16_f32 v102, v138, v139
	ds_read_b64_tr_b16 v[210:211], v218 offset:6144
	ds_read_b64_tr_b16 v[212:213], v218 offset:6656
	v_mfma_f32_32x32x16_bf16 v[48:63], v[166:169], v[88:91], v[48:63]
	v_exp_f32_e32 v247, v247
	v_exp_f32_e32 v145, v145
	v_add_f32_e32 v253, v246, v144
	v_add_f32_e32 v252, v252, v253
	v_cvt_pk_bf16_f32 v111, v242, v243
	v_cvt_pk_bf16_f32 v103, v140, v141
	ds_read_b64_tr_b16 v[214:215], v218 offset:7168
	ds_read_b64_tr_b16 v[216:217], v218 offset:7680
	v_mfma_f32_32x32x16_bf16 v[64:79], v[170:173], v[84:87], v[64:79]
	v_exp_f32_e32 v248, v248
	v_exp_f32_e32 v146, v146
	v_add_f32_e32 v253, v247, v145
	v_add_f32_e32 v252, v252, v253
	v_cvt_pk_bf16_f32 v104, v244, v245
	v_cvt_pk_bf16_f32 v96, v142, v143
	v_mfma_f32_32x32x16_bf16 v[48:63], v[174:177], v[84:87], v[48:63]
	v_exp_f32_e32 v249, v249
	v_exp_f32_e32 v147, v147
	v_add_f32_e32 v253, v248, v146
	v_add_f32_e32 v252, v252, v253
	v_cvt_pk_bf16_f32 v105, v246, v247
	v_cvt_pk_bf16_f32 v97, v144, v145
	v_mfma_f32_32x32x16_bf16 v[64:79], v[178:181], v[80:83], v[64:79]
	v_exp_f32_e32 v250, v250
	v_exp_f32_e32 v148, v148
	v_add_f32_e32 v253, v249, v147
	v_add_f32_e32 v252, v252, v253
	v_cvt_pk_bf16_f32 v106, v248, v249
	v_cvt_pk_bf16_f32 v98, v146, v147
	v_mfma_f32_32x32x16_bf16 v[48:63], v[182:185], v[80:83], v[48:63]
	v_exp_f32_e32 v251, v251
	v_exp_f32_e32 v149, v149
	v_add_f32_e32 v253, v250, v148
	v_add_f32_e32 v252, v252, v253
	v_add_f32_e32 v253, v251, v149
	v_add_f32_e32 v252, v252, v253
	v_cvt_pk_bf16_f32 v107, v250, v251
	v_cvt_pk_bf16_f32 v99, v148, v149
	v_add_f32_e32 v131, v131, v252

; #define ATT_LAS __attribute__((address_space(3)))
; #define ATT_MFMA(a, b, c) __builtin_amdgcn_mfma_f32_32x32x16_bf16((a), (b), (c), 0, 0, 0)
; __device__ __forceinline__ void qkt(f32x16& p0, f32x16& p1, lds_cptr kb, const bf16x8* qr, const f32x16& z) {
; #pragma unroll
;     for (int d0 = 0; d0 < 4; ++d0) {
;         const bf16x8 b0 = *(const ATT_LAS bf16x8*)(kb + d0 * 2048);
;         const bf16x8 b1 = *(const ATT_LAS bf16x8*)(kb + d0 * 2048 + 512);
;         if (d0 == 0) { p0 = ATT_MFMA(b0, qr[0], z); p1 = ATT_MFMA(b1, qr[0], z); }
;         else { p0 = ATT_MFMA(b0, qr[d0], p0); p1 = ATT_MFMA(b1, qr[d0], p1); } }
; }
; __device__ __forceinline__ void pv(f32x16* o, int vb, bf16x8 pa0, bf16x8 pa1, bf16x8 pa2, bf16x8 pa3) {
; #pragma unroll
;     for (int d0 = 0; d0 < 2; ++d0) { s16x4 lo[4], hi[4];
; #pragma unroll
;         for (int ks = 0; ks < 4; ++ks) {
;             asm volatile("ds_read_b64_tr_b16 %0,%1 offset:%c2" : "=&v"(lo[ks]) : "v"(vb), "i"(d0 * 4096 + ks * 1024) : "memory");
;             asm volatile("ds_read_b64_tr_b16 %0,%1 offset:%c2" : "=&v"(hi[ks]) : "v"(vb), "i"(d0 * 4096 + ks * 1024 + 512) : "memory"); }
;         asm volatile("s_waitcnt lgkmcnt(0)" ::: "memory"); __builtin_amdgcn_sched_barrier(0);
;     ...
;         o[d0] = ATT_MFMA(pa0, ATT_PK(0), o[d0]);
;         o[d0] = ATT_MFMA(pa1, ATT_PK(1), o[d0]);
;         o[d0] = ATT_MFMA(pa2, ATT_PK(2), o[d0]);
;         o[d0] = ATT_MFMA(pa3, ATT_PK(3), o[d0]);
;     ...
;     }
; }
.Lmb3_A_g1top:
	s_add_i32 s36, s43, 0x2000
	s_add_i32 s98, s43, 0x4000
	s_and_b32 s42, s98, 0x6000
	v_add_u32_e32 v133, s42, v130
	ds_read_b128 v[154:157], v133
	ds_read_b128 v[158:161], v133 offset:512
	ds_read_b128 v[162:165], v133 offset:2048
	ds_read_b128 v[166:169], v133 offset:2560
	ds_read_b128 v[170:173], v133 offset:4096
	ds_read_b128 v[174:177], v133 offset:4608
	ds_read_b128 v[178:181], v133 offset:6144
	ds_read_b128 v[182:185], v133 offset:6656
	s_and_b32 s42, s36, 0x6000
	v_add_u32_e32 v218, s42, v132
	s_add_i32 s98, s30, 2
	s_cmp_ge_i32 s30, s29
	s_cbranch_scc1 .Lmb3_A_near
	v_mfma_f32_32x32x16_bf16 v[16:31], v[108:111], v[186:189], v[16:31]
	v_exp_f32_e32 v64, v64
	v_exp_f32_e32 v48, v48
	v_mfma_f32_32x32x16_bf16 v[16:31], v[104:107], v[190:193], v[16:31]
	v_exp_f32_e32 v65, v65
	v_exp_f32_e32 v49, v49
	v_add_f32_e32 v252, v64, v48
	s_and_b64 vcc, exec, s[6:7]
	s_cbranch_vccnz .Lmb3_A_g0mid
	s_cmp_eq_u32 s35, 0
	s_cbranch_scc1 .Lmb3_f1Am
	s_mov_b32 s42, s35
	s_cmp_ge_u32 s42, s28
	s_cbranch_scc1 .Lmb3_k0Am
	s_mov_b32 s42, s43
	s_and_b32 s42, s42, 0x6000
	s_add_i32 s42, s42, s74
	s_mov_b32 s99, m0
	s_mov_b32 m0, s42
	s_nop 0
	global_load_lds_dwordx4 v[114:115], off
	s_mov_b32 m0, s99

; #define ATT_LAS __attribute__((address_space(3)))
; #define ATT_MFMA(a, b, c) __builtin_amdgcn_mfma_f32_32x32x16_bf16((a), (b), (c), 0, 0, 0)
; __device__ __forceinline__ void qkt(f32x16& p0, f32x16& p1, lds_cptr kb, const bf16x8* qr, const f32x16& z) {
; #pragma unroll
;     for (int d0 = 0; d0 < 4; ++d0) {
;         const bf16x8 b0 = *(const ATT_LAS bf16x8*)(kb + d0 * 2048);
;         const bf16x8 b1 = *(const ATT_LAS bf16x8*)(kb + d0 * 2048 + 512);
;         if (d0 == 0) { p0 = ATT_MFMA(b0, qr[0], z); p1 = ATT_MFMA(b1, qr[0], z); }
;         else { p0 = ATT_MFMA(b0, qr[d0], p0); p1 = ATT_MFMA(b1, qr[d0], p1); } }
; }
; __device__ __forceinline__ void pv(f32x16* o, int vb, bf16x8 pa0, bf16x8 pa1, bf16x8 pa2, bf16x8 pa3) {
; #pragma unroll
.Lmb3_B_g1top:
	s_add_i32 s36, s43, 0x2000
	s_add_i32 s98, s43, 0x4000
	s_and_b32 s42, s98, 0x6000
	v_add_u32_e32 v133, s42, v130
	ds_read_b128 v[154:157], v133
	ds_read_b128 v[158:161], v133 offset:512
	ds_read_b128 v[162:165], v133 offset:2048
	ds_read_b128 v[166:169], v133 offset:2560
	ds_read_b128 v[170:173], v133 offset:4096
	ds_read_b128 v[174:177], v133 offset:4608
	ds_read_b128 v[178:181], v133 offset:6144
	ds_read_b128 v[182:185], v133 offset:6656
	s_and_b32 s42, s36, 0x6000
	v_add_u32_e32 v218, s42, v132
	s_add_i32 s98, s30, 2
	s_cmp_ge_i32 s30, s29
	s_cbranch_scc1 .Lmb3_B_near
	v_mfma_f32_32x32x16_bf16 v[16:31], v[108:111], v[186:189], v[16:31]
	v_exp_f32_e32 v236, v236
	v_exp_f32_e32 v134, v134
	v_mfma_f32_32x32x16_bf16 v[16:31], v[104:107], v[190:193], v[16:31]
	v_exp_f32_e32 v237, v237
	v_exp_f32_e32 v135, v135
	v_add_f32_e32 v252, v236, v134
	s_and_b64 vcc, exec, s[6:7]
	s_cbranch_vccnz .Lmb3_B_g0mid
